# PREP gates_tiles: tiles spread over all non-compress workgroups (4-5 per workgroup) instead of 8 per workgroup on the upper half
# baseline (speedup 1.0000x reference)
; __device__ __forceinline__ void gates_tiles(const Frame& F, int l, int wg0) {
;     const int NGW = (F.G - wg0) * NWAVES, gw = NGW - 1 - ((F.bid - wg0) * NWAVES + F.wave), fr = F.lane & 15, fq = F.lane >> 4;
;     const bf16* H = (const bf16*)(F.ws + WS_H); const bf16* WG = (const bf16*)(F.ws + WS_WIN) + ((size_t)l * NINP + 3072) * D;
;     for (int rt = gw; rt < T / 16; rt += NGW) {
;         f32x4 a0 = {0.f, 0.f, 0.f, 0.f}, a1 = {0.f, 0.f, 0.f, 0.f};
;         const bf16* ap = H + (size_t)(16 * rt + fr) * D + 8 * fq; const bf16* bp = WG + (size_t)fr * D + 8 * fq;
.LBB0_1336:
	s_sub_i32 s0, s81, s74
	s_sub_i32 s0, s80, s0
	s_mul_i32 s3, s74, s8
	s_add_i32 s3, s3, s0
	s_cmpk_gt_i32 s3, 0x3ff
	s_barrier
	s_cbranch_scc1 .LBB0_1345
	v_and_b32_e32 v198, 48, v1
	v_lshl_add_u64 v[2:3], s[78:79], 0, v[198:199]
	s_mov_b64 s[4:5], 0x6f000000
	s_waitcnt vmcnt(27)
	v_lshl_add_u64 v[10:11], v[2:3], 0, s[4:5]
	v_readlane_b32 s4, v249, 28
	v_cmp_gt_u32_e64 s[0:1], 32, v1
	v_lshlrev_b32_e32 v2, 11, v5
	s_waitcnt vmcnt(20)
	v_add_u32_e32 v1, s4, v24
	s_lshl_b32 s4, s8, 4
	v_subrev_u32_e32 v14, s4, v1
	s_lshl_b32 s4, s3, 4
	v_add_u32_e32 v14, s4, v24
	v_readlane_b32 s4, v249, 39
	v_mov_b32_e32 v3, v199
	v_readlane_b32 s5, v249, 40
	v_and_b32_e32 v198, 48, v0
	v_lshl_add_u64 v[12:13], s[78:79], 0, v[198:199]
	v_lshl_add_u64 v[2:3], s[4:5], 0, v[2:3]
	v_lshl_add_u64 v[2:3], v[2:3], 0, v[198:199]
	v_lshl_add_u64 v[16:17], s[78:79], 0, v[2:3]
	s_branch .LBB0_1339
